# v16 + one static s_setprio 1 for waves 4-7 during the attention phase (strategy 4)
# speedup vs baseline: 1.0135x; 1.0017x over previous
; DI void phase_attn(int l, half_t* big, bool need_ctx, char* smem, int wv_) {
;     ...
;   const float lam_init = 0.8f - 0.6f * expf(-0.3f * (float)l);
;   float lam;
;   {
;     float d1 = 0.f, d2 = 0.f;
; #pragma unroll 1
;     for (int i = 0; i < 32; ++i) {
;       d1 += p->lq1[l * 32 + i] * p->lk1[l * 32 + i];
;       d2 += p->lq2[l * 32 + i] * p->lk2[l * 32 + i];
;     }
;     lam = expf(d1) - expf(d2) + lam_init;
;     lam = __builtin_bit_cast(float, __builtin_amdgcn_readfirstlane(__builtin_bit_cast(int, lam)));
.LBB0_1899:
	s_or_b64 exec, exec, s[60:61]
	s_mov_b64 s[10:11], s[0:1]
	s_waitcnt lgkmcnt(0)
	s_barrier
	s_cmp_ge_u32 s55, 0x100
	s_cbranch_scc0 .Lp4prio_lo
	s_setprio 1
.Lp4prio_lo:
	s_load_dwordx8 s[12:19], s[10:11], 0xa0
	s_lshl_b64 s[2:3], s[52:53], 7
	s_waitcnt vmcnt(0)
	v_mov_b32_e32 v3, 0
	v_mov_b32_e32 v2, 0
	s_waitcnt lgkmcnt(0)
	s_add_u32 s4, s18, s2
	s_addc_u32 s5, s19, s3
	s_add_u32 s6, s16, s2
	s_addc_u32 s7, s17, s3
	s_add_u32 s8, s14, s2
	s_addc_u32 s9, s15, s3
	s_add_u32 s12, s12, s2
	s_addc_u32 s13, s13, s3
	global_load_dword v32, v0, s[12:13] offset:0
	global_load_dword v34, v0, s[8:9] offset:0
	global_load_dword v33, v0, s[6:7] offset:0
	global_load_dword v35, v0, s[4:5] offset:0
	global_load_dword v36, v0, s[12:13] offset:4
	global_load_dword v38, v0, s[8:9] offset:4
	global_load_dword v37, v0, s[6:7] offset:4
	global_load_dword v39, v0, s[4:5] offset:4
	global_load_dword v40, v0, s[12:13] offset:8
	global_load_dword v42, v0, s[8:9] offset:8
	global_load_dword v41, v0, s[6:7] offset:8
	global_load_dword v43, v0, s[4:5] offset:8
	global_load_dword v44, v0, s[12:13] offset:12
	global_load_dword v46, v0, s[8:9] offset:12
	global_load_dword v45, v0, s[6:7] offset:12
	global_load_dword v47, v0, s[4:5] offset:12
	global_load_dword v48, v0, s[12:13] offset:16
	global_load_dword v50, v0, s[8:9] offset:16
	global_load_dword v49, v0, s[6:7] offset:16
	global_load_dword v51, v0, s[4:5] offset:16
	global_load_dword v52, v0, s[12:13] offset:20
	global_load_dword v54, v0, s[8:9] offset:20
	global_load_dword v53, v0, s[6:7] offset:20
	global_load_dword v55, v0, s[4:5] offset:20
	global_load_dword v56, v0, s[12:13] offset:24
	global_load_dword v58, v0, s[8:9] offset:24
	global_load_dword v57, v0, s[6:7] offset:24
	global_load_dword v59, v0, s[4:5] offset:24
	global_load_dword v60, v0, s[12:13] offset:28
	global_load_dword v62, v0, s[8:9] offset:28
	global_load_dword v61, v0, s[6:7] offset:28
	global_load_dword v63, v0, s[4:5] offset:28
	global_load_dword v64, v0, s[12:13] offset:32
	global_load_dword v66, v0, s[8:9] offset:32
	global_load_dword v65, v0, s[6:7] offset:32
	global_load_dword v67, v0, s[4:5] offset:32
	global_load_dword v68, v0, s[12:13] offset:36
	global_load_dword v70, v0, s[8:9] offset:36
	global_load_dword v69, v0, s[6:7] offset:36
	global_load_dword v71, v0, s[4:5] offset:36
	global_load_dword v72, v0, s[12:13] offset:40
	global_load_dword v74, v0, s[8:9] offset:40
	global_load_dword v73, v0, s[6:7] offset:40
	global_load_dword v75, v0, s[4:5] offset:40
	global_load_dword v76, v0, s[12:13] offset:44
	global_load_dword v78, v0, s[8:9] offset:44
	global_load_dword v77, v0, s[6:7] offset:44
	global_load_dword v79, v0, s[4:5] offset:44
	global_load_dword v144, v0, s[12:13] offset:48
	global_load_dword v146, v0, s[8:9] offset:48
	global_load_dword v145, v0, s[6:7] offset:48
	global_load_dword v147, v0, s[4:5] offset:48
	global_load_dword v148, v0, s[12:13] offset:52
	global_load_dword v150, v0, s[8:9] offset:52
	global_load_dword v149, v0, s[6:7] offset:52
	global_load_dword v151, v0, s[4:5] offset:52
	global_load_dword v152, v0, s[12:13] offset:56
	global_load_dword v154, v0, s[8:9] offset:56
	global_load_dword v153, v0, s[6:7] offset:56
	global_load_dword v155, v0, s[4:5] offset:56
	global_load_dword v156, v0, s[12:13] offset:60
	global_load_dword v158, v0, s[8:9] offset:60
	global_load_dword v157, v0, s[6:7] offset:60
	global_load_dword v159, v0, s[4:5] offset:60
	global_load_dword v160, v0, s[12:13] offset:64
	global_load_dword v162, v0, s[8:9] offset:64
	global_load_dword v161, v0, s[6:7] offset:64
	global_load_dword v163, v0, s[4:5] offset:64
	global_load_dword v164, v0, s[12:13] offset:68
	global_load_dword v166, v0, s[8:9] offset:68
	global_load_dword v165, v0, s[6:7] offset:68
	global_load_dword v167, v0, s[4:5] offset:68
	global_load_dword v168, v0, s[12:13] offset:72
	global_load_dword v170, v0, s[8:9] offset:72
	global_load_dword v169, v0, s[6:7] offset:72
	global_load_dword v171, v0, s[4:5] offset:72
	global_load_dword v172, v0, s[12:13] offset:76
	global_load_dword v174, v0, s[8:9] offset:76
	global_load_dword v173, v0, s[6:7] offset:76
	global_load_dword v175, v0, s[4:5] offset:76
	global_load_dword v176, v0, s[12:13] offset:80
	global_load_dword v178, v0, s[8:9] offset:80
	global_load_dword v177, v0, s[6:7] offset:80
	global_load_dword v179, v0, s[4:5] offset:80
	global_load_dword v180, v0, s[12:13] offset:84
	global_load_dword v182, v0, s[8:9] offset:84
	global_load_dword v181, v0, s[6:7] offset:84
	global_load_dword v183, v0, s[4:5] offset:84
	global_load_dword v184, v0, s[12:13] offset:88
	global_load_dword v186, v0, s[8:9] offset:88
	global_load_dword v185, v0, s[6:7] offset:88
	global_load_dword v187, v0, s[4:5] offset:88
	global_load_dword v188, v0, s[12:13] offset:92
	global_load_dword v190, v0, s[8:9] offset:92
	global_load_dword v189, v0, s[6:7] offset:92
	global_load_dword v191, v0, s[4:5] offset:92
	global_load_dword v192, v0, s[12:13] offset:96
	global_load_dword v194, v0, s[8:9] offset:96
	global_load_dword v193, v0, s[6:7] offset:96
	global_load_dword v195, v0, s[4:5] offset:96
	global_load_dword v196, v0, s[12:13] offset:100
	global_load_dword v198, v0, s[8:9] offset:100
	global_load_dword v197, v0, s[6:7] offset:100
	global_load_dword v199, v0, s[4:5] offset:100
	global_load_dword v200, v0, s[12:13] offset:104
	global_load_dword v202, v0, s[8:9] offset:104
	global_load_dword v201, v0, s[6:7] offset:104
	global_load_dword v203, v0, s[4:5] offset:104
	global_load_dword v204, v0, s[12:13] offset:108
	global_load_dword v206, v0, s[8:9] offset:108
	global_load_dword v205, v0, s[6:7] offset:108
	global_load_dword v207, v0, s[4:5] offset:108
	global_load_dword v208, v0, s[12:13] offset:112
	global_load_dword v210, v0, s[8:9] offset:112
	global_load_dword v209, v0, s[6:7] offset:112
	global_load_dword v211, v0, s[4:5] offset:112
	global_load_dword v212, v0, s[12:13] offset:116
	global_load_dword v214, v0, s[8:9] offset:116
	global_load_dword v213, v0, s[6:7] offset:116
	global_load_dword v215, v0, s[4:5] offset:116
	global_load_dword v216, v0, s[12:13] offset:120
	global_load_dword v218, v0, s[8:9] offset:120
	global_load_dword v217, v0, s[6:7] offset:120
	global_load_dword v219, v0, s[4:5] offset:120
	global_load_dword v220, v0, s[12:13] offset:124
	global_load_dword v222, v0, s[8:9] offset:124
	global_load_dword v221, v0, s[6:7] offset:124
	global_load_dword v223, v0, s[4:5] offset:124
	s_waitcnt vmcnt(0)
; DI void phase_attn(int l, half_t* big, bool need_ctx, char* smem, int wv_) {
;     ...
;   const float lam_init = 0.8f - 0.6f * expf(-0.3f * (float)l);
;   float lam;
;   {
;     float d1 = 0.f, d2 = 0.f;
; #pragma unroll 1
;     for (int i = 0; i < 32; ++i) {
;       d1 += p->lq1[l * 32 + i] * p->lk1[l * 32 + i];
;       d2 += p->lq2[l * 32 + i] * p->lk2[l * 32 + i];
;     }
;     lam = expf(d1) - expf(d2) + lam_init;
;     lam = __builtin_bit_cast(float, __builtin_amdgcn_readfirstlane(__builtin_bit_cast(int, lam)));
;   }
;   const float one_m_li = __builtin_bit_cast(float, __builtin_amdgcn_readfirstlane(__builtin_bit_cast(int, 1.f - lam_init)));
;   const int per = 4 * 16 * NQB;
	v_pk_fma_f32 v[2:3], v[32:33], v[34:35], v[2:3]
	v_pk_fma_f32 v[2:3], v[36:37], v[38:39], v[2:3]
	v_pk_fma_f32 v[2:3], v[40:41], v[42:43], v[2:3]
	v_pk_fma_f32 v[2:3], v[44:45], v[46:47], v[2:3]
	v_pk_fma_f32 v[2:3], v[48:49], v[50:51], v[2:3]
	v_pk_fma_f32 v[2:3], v[52:53], v[54:55], v[2:3]
	v_pk_fma_f32 v[2:3], v[56:57], v[58:59], v[2:3]
	v_pk_fma_f32 v[2:3], v[60:61], v[62:63], v[2:3]
	v_pk_fma_f32 v[2:3], v[64:65], v[66:67], v[2:3]
	v_pk_fma_f32 v[2:3], v[68:69], v[70:71], v[2:3]
	v_pk_fma_f32 v[2:3], v[72:73], v[74:75], v[2:3]
	v_pk_fma_f32 v[2:3], v[76:77], v[78:79], v[2:3]
	v_pk_fma_f32 v[2:3], v[144:145], v[146:147], v[2:3]
	v_pk_fma_f32 v[2:3], v[148:149], v[150:151], v[2:3]
	v_pk_fma_f32 v[2:3], v[152:153], v[154:155], v[2:3]
	v_pk_fma_f32 v[2:3], v[156:157], v[158:159], v[2:3]
	v_pk_fma_f32 v[2:3], v[160:161], v[162:163], v[2:3]
	v_pk_fma_f32 v[2:3], v[164:165], v[166:167], v[2:3]
	v_pk_fma_f32 v[2:3], v[168:169], v[170:171], v[2:3]
	v_pk_fma_f32 v[2:3], v[172:173], v[174:175], v[2:3]
	v_pk_fma_f32 v[2:3], v[176:177], v[178:179], v[2:3]
	v_pk_fma_f32 v[2:3], v[180:181], v[182:183], v[2:3]
	v_pk_fma_f32 v[2:3], v[184:185], v[186:187], v[2:3]
	v_pk_fma_f32 v[2:3], v[188:189], v[190:191], v[2:3]
	v_pk_fma_f32 v[2:3], v[192:193], v[194:195], v[2:3]
	v_pk_fma_f32 v[2:3], v[196:197], v[198:199], v[2:3]
	v_pk_fma_f32 v[2:3], v[200:201], v[202:203], v[2:3]
	v_pk_fma_f32 v[2:3], v[204:205], v[206:207], v[2:3]
	v_pk_fma_f32 v[2:3], v[208:209], v[210:211], v[2:3]
	v_pk_fma_f32 v[2:3], v[212:213], v[214:215], v[2:3]
	v_pk_fma_f32 v[2:3], v[216:217], v[218:219], v[2:3]
	v_pk_fma_f32 v[2:3], v[220:221], v[222:223], v[2:3]
	v_cvt_f32_u32_e32 v1, s52
	s_mov_b32 s2, 0x3fb8aa3b
	s_mov_b32 s3, 0xc2ce8ed0
	s_mov_b32 s4, 0x42b17218
	v_mul_f32_e32 v1, 0xbe99999a, v1
	v_mul_f32_e32 v4, 0x3fb8aa3b, v1
	v_fma_f32 v5, v1, s2, -v4
	v_rndne_f32_e32 v6, v4
	v_fmac_f32_e32 v5, 0x32a5705f, v1
	v_sub_f32_e32 v4, v4, v6
	v_add_f32_e32 v4, v4, v5
	v_exp_f32_e32 v4, v4
	v_cvt_i32_f32_e32 v5, v6
	v_cmp_ngt_f32_e32 vcc, s3, v1
	v_mov_b32_e32 v7, 0x7f800000
	s_mov_b32 s34, 0
	v_ldexp_f32 v4, v4, v5
	v_cndmask_b32_e32 v4, 0, v4, vcc
	v_cmp_nlt_f32_e32 vcc, s4, v1
	s_nop 1
	v_cndmask_b32_e32 v1, v7, v4, vcc
	v_mov_b32_e32 v4, 0x3f4ccccd
	v_fmamk_f32 v1, v1, 0xbf19999a, v4
	v_mul_f32_e32 v4, 0x3fb8aa3b, v2
	v_rndne_f32_e32 v5, v4
	v_sub_f32_e32 v6, v4, v5
	v_fma_f32 v4, v2, s2, -v4
	v_fmac_f32_e32 v4, 0x32a5705f, v2
	v_add_f32_e32 v4, v6, v4
	v_exp_f32_e32 v4, v4
	v_cvt_i32_f32_e32 v5, v5
	v_cmp_ngt_f32_e32 vcc, s3, v2
	v_ldexp_f32 v4, v4, v5
	s_nop 0
	v_cndmask_b32_e32 v4, 0, v4, vcc
	v_cmp_nlt_f32_e32 vcc, s4, v2
	s_nop 1
	v_cndmask_b32_e32 v2, v7, v4, vcc
	v_mul_f32_e32 v4, 0x3fb8aa3b, v3
	v_rndne_f32_e32 v5, v4
	v_sub_f32_e32 v6, v4, v5
	v_fma_f32 v4, v3, s2, -v4
	v_fmac_f32_e32 v4, 0x32a5705f, v3
	v_add_f32_e32 v4, v6, v4
	v_exp_f32_e32 v4, v4
	v_cvt_i32_f32_e32 v5, v5
	v_cmp_ngt_f32_e32 vcc, s3, v3
	v_readfirstlane_b32 s2, v1
	v_ldexp_f32 v4, v4, v5
	v_cndmask_b32_e32 v4, 0, v4, vcc
	v_cmp_nlt_f32_e32 vcc, s4, v3
	v_sub_f32_e64 v238, 1.0, s2
	v_readlane_b32 s2, v254, 57
	v_cndmask_b32_e32 v3, v7, v4, vcc
	v_sub_f32_e32 v2, v2, v3
	v_readlane_b32 s3, v254, 58
	v_add_f32_e32 v2, v1, v2
	s_and_b64 s[2:3], s[2:3], exec
	v_readfirstlane_b32 s12, v2
	s_movk_i32 s2, 0x140
	s_cselect_b32 s30, s2, 0x100
	s_lshl_b32 s31, s52, 2
	s_mov_b32 s13, s12
	s_branch .LBB0_1903

; #define LAS __attribute__((address_space(3)))
; DI unsigned xb_xcc_id() { return (unsigned)__builtin_amdgcn_s_getreg((3 << 11) | 20) & 0xFu; }
; DI void xcd_barrier(char* ws_, LAS unsigned char* lds_, int wv_) {
;   asm volatile("s_waitcnt vmcnt(0)" ::: "memory");
;   __syncthreads();
;   if (tid_opaque(wv_) == 0) {
;     char* wsl = ws_;
;     asm volatile("" : "+s"(wsl));
;     unsigned* bar = (unsigned*)(wsl + OFF_BAR);
;     volatile LAS unsigned* st = (volatile LAS unsigned*)(lds_ + GEMM_LDS);
;     const unsigned x = xb_xcc_id();
;     __builtin_amdgcn_s_waitcnt(0);
;     unsigned nloc = st[0], nx = st[1];
;     if (nloc == 0u) { xcd_barrier_complete(bar, x, nloc, nx); st[0] = nloc; st[1] = nx; }
.LBB0_2212:
	s_setprio 0
	s_waitcnt lgkmcnt(1)
	v_mov_b32_e32 v1, v0
	s_waitcnt vmcnt(0)
	s_waitcnt lgkmcnt(0)
	s_barrier
	s_nop 0
	v_mbcnt_lo_u32_b32 v1, -1, v1
	v_mbcnt_hi_u32_b32 v1, -1, v1
	v_or_b32_e32 v1, s55, v1
	s_nop 0
	v_cmp_eq_u32_e32 vcc, 0, v1
	s_mov_b64 s[36:37], exec
	s_and_b64 s[2:3], s[36:37], vcc
	v_mov_b32_e32 v222, 0x358637bd
	v_mov_b32_e32 v223, 0x20000
	v_mov_b32_e32 v224, 0x20004
	v_mov_b32_e32 v225, 1
	v_mov_b32_e32 v226, 0x3c0881c4
	v_mov_b32_e32 v227, 0xbab64f3b
	v_xor_b32_e32 v228, 8, v240
	v_xor_b32_e32 v229, 4, v240
	v_xor_b32_e32 v230, 2, v240
	v_xor_b32_e32 v231, 1, v240
	v_mov_b32_e32 v232, 0x18000
	v_mov_b32_e32 v233, 0x3fd49a78
	v_mov_b32_e32 v234, 0x3f549a78
	v_mov_b32_e32 v235, 0x42800000
	v_not_b32_e32 v236, 63
	v_not_b32_e32 v237, 31
	v_mov_b32_e32 v238, 0x7fc00000
	s_mov_b64 exec, s[2:3]
	s_cbranch_execz .LBB0_2256
	v_readlane_b32 s34, v253, 0
	v_readlane_b32 s35, v253, 1
	s_getreg_b32 s2, hwreg(HW_REG_XCC_ID, 0, 4)
	s_waitcnt vmcnt(0) expcnt(0) lgkmcnt(0)
	ds_read_b32 v4, v223
	ds_read_b32 v2, v224
	s_and_b32 s46, s2, 15
	s_waitcnt lgkmcnt(1)
	v_cmp_ne_u32_e32 vcc, 0, v4
	s_cbranch_vccnz .LBB0_2227
	v_readlane_b32 s2, v253, 2
	v_readlane_b32 s3, v253, 3
	s_load_dwordx2 s[6:7], s[2:3], 0x4
	s_add_u32 s2, s34, 0x1000
	s_addc_u32 s3, s35, 0
	s_add_u32 s4, s34, 0x1100
	s_addc_u32 s5, s35, 0
	s_waitcnt lgkmcnt(0)
	s_mul_i32 s28, s6, s54
	s_add_u32 s6, s34, 0x1200
	s_mul_i32 s28, s28, s7
	s_addc_u32 s7, s35, 0
	s_add_u32 s8, s34, 0x1300
	s_addc_u32 s9, s35, 0
	s_mov_b32 s29, 1
	s_mov_b64 s[10:11], 0
	s_branch .LBB0_2217
